# gate->weight-conversion seam of layers 0 and 2: control-only all-groups-arrived check (WAR only) instead of the grid barrier
# speedup vs baseline: 1.0198x; 1.0032x over previous
.Lmy_gchk_4:
	s_mov_b32 s2, -1
	s_nop 0
	v_mbcnt_lo_u32_b32 v0, s2, 0
	v_mbcnt_hi_u32_b32 v0, s2, v0
	s_nop 0
	v_cmp_eq_u32_e32 vcc, 0, v0
	s_and_saveexec_b64 s[16:17], vcc
	s_cbranch_execz .LBB0_905
	s_cmp_lg_u32 s101, 1
	s_cbranch_scc1 .Lmy_gfull_4
	v_readlane_b32 s2, v253, 37
	v_readlane_b32 s3, v250, 7
	v_readlane_b32 s8, v250, 0
	v_readlane_b32 s9, v250, 1
	s_lshl_b32 s2, s2, 12
	s_add_i32 s2, s2, 0x4000
	s_and_b32 s3, s3, 63
	s_lshl_b32 s3, s3, 6
	s_add_i32 s2, s2, s3
	s_add_u32 s8, s8, 0x70000
	s_addc_u32 s9, s9, 0
	v_mov_b32_e32 v0, s2
	v_mov_b32_e32 v1, 1
	s_waitcnt vmcnt(0) lgkmcnt(0)
	global_atomic_add v0, v1, s[8:9]
	s_mov_b32 s2, 0

.Lmy_gchk_7:
	s_mov_b32 s0, -1
	s_nop 0
	v_mbcnt_lo_u32_b32 v0, s0, 0
	v_mbcnt_hi_u32_b32 v0, s0, v0
	s_nop 0
	v_cmp_eq_u32_e32 vcc, 0, v0
	s_and_saveexec_b64 s[18:19], vcc
	s_cbranch_execz .LBB0_1297
	s_cmp_lg_u32 s101, 1
	s_cbranch_scc1 .Lmy_gfull_7
	v_readlane_b32 s2, v253, 37
	v_readlane_b32 s3, v250, 7
	v_readlane_b32 s8, v250, 0
	v_readlane_b32 s9, v250, 1
	s_lshl_b32 s2, s2, 12
	s_add_i32 s2, s2, 0x7000
	s_and_b32 s3, s3, 63
	s_lshl_b32 s3, s3, 6
	s_add_i32 s2, s2, s3
	s_add_u32 s8, s8, 0x70000
	s_addc_u32 s9, s9, 0
	v_mov_b32_e32 v0, s2
	v_mov_b32_e32 v1, 1
	s_waitcnt vmcnt(0) lgkmcnt(0)
	global_atomic_add v0, v1, s[8:9]
	s_mov_b32 s2, 0

.Lmy_gchk_0:
	s_mov_b32 s2, -1
	s_nop 0
	v_mbcnt_lo_u32_b32 v0, s2, 0
	v_mbcnt_hi_u32_b32 v0, s2, v0
	s_nop 0
	v_cmp_eq_u32_e32 vcc, 0, v0
	s_and_saveexec_b64 s[16:17], vcc
	s_cbranch_execz .LBB0_1954
	s_cmp_lg_u32 s101, 1
	s_cbranch_scc1 .Lmy_gfull_0
	v_readlane_b32 s2, v253, 37
	v_readlane_b32 s3, v250, 7
	v_readlane_b32 s8, v250, 0
	v_readlane_b32 s9, v250, 1
	s_lshl_b32 s2, s2, 12
	s_add_i32 s2, s2, 0x0
	s_and_b32 s3, s3, 63
	s_lshl_b32 s3, s3, 6
	s_add_i32 s2, s2, s3
	s_add_u32 s8, s8, 0x70000
	s_addc_u32 s9, s9, 0
	v_mov_b32_e32 v0, s2
	v_mov_b32_e32 v1, 1
	s_waitcnt vmcnt(0) lgkmcnt(0)
	global_atomic_add v0, v1, s[8:9]
	s_mov_b32 s2, 0

.Lmy_gchk_3:
	s_mov_b32 s2, -1
	s_nop 0
	v_mbcnt_lo_u32_b32 v0, s2, 0
	v_mbcnt_hi_u32_b32 v0, s2, v0
	s_nop 0
	v_cmp_eq_u32_e32 vcc, 0, v0
	s_and_saveexec_b64 s[16:17], vcc
	s_cbranch_execz .LBB0_2032
	s_cmp_lg_u32 s101, 1
	s_cbranch_scc1 .Lmy_gfull_3
	v_readlane_b32 s100, v253, 37
	v_readlane_b32 s3, v250, 7
	v_readlane_b32 s8, v250, 0
	v_readlane_b32 s9, v250, 1
	s_lshl_b32 s12, s100, 12
	s_add_i32 s2, s12, 0x3000
	s_and_b32 s13, s3, 63
	s_lshl_b32 s13, s13, 6
	s_add_i32 s2, s2, s13
	s_add_u32 s8, s8, 0x70000
	s_addc_u32 s9, s9, 0
	v_mov_b32_e32 v0, s2
	v_mov_b32_e32 v1, 1
	s_waitcnt vmcnt(0) lgkmcnt(0)
	global_atomic_add v0, v1, s[8:9]
	s_mov_b32 s2, 0

.LBB0_2100:
	v_readlane_b32 s0, v253, 37
	v_readlane_b32 s16, v250, 0
	s_or_b32 s0, s0, 12
	v_readlane_b32 s19, v250, 3
	s_cmp_ge_i32 s0, s19
	v_readlane_b32 s17, v250, 1
	v_readlane_b32 s18, v250, 2
	s_cbranch_scc1 .LBB0_2156
	s_waitcnt vmcnt(0)
	v_readlane_b32 s2, v253, 40
	v_readlane_b32 s3, v253, 41
	s_and_b64 vcc, exec, s[2:3]
	s_waitcnt vmcnt(0) lgkmcnt(0)
	s_barrier
	s_cbranch_vccnz .LBB0_2155
	s_mov_b32 s2, -1
	s_nop 0
	v_mbcnt_lo_u32_b32 v0, s2, 0
	v_mbcnt_hi_u32_b32 v0, s2, v0
	s_nop 0
	v_cmp_eq_u32_e32 vcc, 0, v0
	s_and_saveexec_b64 s[16:17], vcc
	s_cbranch_execz .LBB0_2154
	s_cmp_lg_u32 s101, 1
	s_cbranch_scc1 .Lmy_gfull_6
	v_readlane_b32 s2, v253, 37
	v_readlane_b32 s3, v250, 7
	v_readlane_b32 s8, v250, 0
	v_readlane_b32 s9, v250, 1
	s_lshl_b32 s2, s2, 12
	s_add_i32 s2, s2, 0x6000
	s_add_u32 s8, s8, 0x70000
	s_addc_u32 s9, s9, 0
	s_and_b32 s12, s3, 7
	s_lshl_b32 s12, s12, 3
	s_bfe_u32 s13, s3, 0x30003
	s_or_b32 s12, s12, s13
	s_and_b32 s13, s12, 7
	s_cmp_lg_u32 s13, 7
	s_cbranch_scc1 .Lmy_g6_nowb
	s_and_b32 s13, s12, 31
	s_cmp_eq_u32 s13, 31
	s_cbranch_scc1 .Lmy_g6_nowb
	s_waitcnt vmcnt(0) lgkmcnt(0)
	buffer_wbl2 sc1
	s_waitcnt vmcnt(0)

.Lmy_gchk_5:
	s_mov_b32 s2, -1
	s_nop 0
	v_mbcnt_lo_u32_b32 v0, s2, 0
	v_mbcnt_hi_u32_b32 v0, s2, v0
	s_nop 0
	v_cmp_eq_u32_e32 vcc, 0, v0
	s_and_saveexec_b64 s[16:17], vcc
	s_cbranch_execz .LBB0_2218
	s_cmp_lg_u32 s101, 1
	s_cbranch_scc1 .Lmy_gfull_5
	v_readlane_b32 s2, v253, 37
	v_readlane_b32 s3, v250, 7
	v_readlane_b32 s8, v250, 0
	v_readlane_b32 s9, v250, 1
	s_lshl_b32 s2, s2, 12
	s_add_i32 s2, s2, 0x5000
	s_and_b32 s3, s3, 63
	s_lshl_b32 s3, s3, 6
	s_add_i32 s2, s2, s3
	s_add_u32 s8, s8, 0x70000
	s_addc_u32 s9, s9, 0
	v_mov_b32_e32 v0, s2
	v_mov_b32_e32 v1, 1
	s_waitcnt vmcnt(0) lgkmcnt(0)
	global_atomic_add v0, v1, s[8:9]
	s_mov_b32 s2, 0

.Lmy_gchk_1:
	s_mov_b32 s2, -1
	s_nop 0
	v_mbcnt_lo_u32_b32 v0, s2, 0
	v_mbcnt_hi_u32_b32 v0, s2, v0
	s_nop 0
	v_cmp_eq_u32_e32 vcc, 0, v0
	s_and_saveexec_b64 s[16:17], vcc
	s_cbranch_execz .LBB0_2303
	s_cmp_lg_u32 s101, 1
	s_cbranch_scc1 .Lmy_gfull_1
	v_readlane_b32 s2, v253, 37
	v_readlane_b32 s3, v250, 7
	v_readlane_b32 s8, v250, 0
	v_readlane_b32 s9, v250, 1
	s_lshl_b32 s2, s2, 12
	s_add_i32 s2, s2, 0x1000
	s_and_b32 s3, s3, 63
	s_lshl_b32 s3, s3, 6
	s_add_i32 s2, s2, s3
	s_add_u32 s8, s8, 0x70000
	s_addc_u32 s9, s9, 0
	v_mov_b32_e32 v0, s2
	v_mov_b32_e32 v1, 1
	s_waitcnt vmcnt(0) lgkmcnt(0)
	global_atomic_add v0, v1, s[8:9]
	s_mov_b32 s2, 0

.Lmy_gchk_2:
	s_mov_b32 s2, -1
	s_nop 0
	v_mbcnt_lo_u32_b32 v0, s2, 0
	v_mbcnt_hi_u32_b32 v0, s2, v0
	s_nop 0
	v_cmp_eq_u32_e32 vcc, 0, v0
	s_and_saveexec_b64 s[16:17], vcc
	s_cbranch_execz .LBB0_2381
	s_cmp_lg_u32 s101, 1
	s_cbranch_scc1 .Lmy_gfull_2
	v_readlane_b32 s2, v253, 37
	v_readlane_b32 s3, v250, 7
	v_readlane_b32 s8, v250, 0
	v_readlane_b32 s9, v250, 1
	s_lshl_b32 s2, s2, 12
	s_add_i32 s2, s2, 0x2000
	s_and_b32 s3, s3, 63
	s_lshl_b32 s3, s3, 6
	s_add_i32 s2, s2, s3
	s_add_u32 s8, s8, 0x70000
	s_addc_u32 s9, s9, 0
	v_mov_b32_e32 v0, s2
	v_mov_b32_e32 v1, 1
	s_waitcnt vmcnt(0) lgkmcnt(0)
	global_atomic_add v0, v1, s[8:9]
	s_mov_b32 s2, 0

.LBB0_2510:
	s_cmp_lg_u32 s101, 1
	s_cbranch_scc1 .Lmy_gfull_8
	v_readlane_b32 s100, v253, 37
	s_cmp_eq_u32 s100, 16
	s_cbranch_scc1 .Lmy_gfull_8
	v_readlane_b32 s3, v250, 7
	v_readlane_b32 s8, v250, 0
	v_readlane_b32 s9, v250, 1
	s_lshl_b32 s12, s100, 12
	s_add_i32 s12, s12, 0x8000
	s_and_b32 s13, s3, 63
	s_lshl_b32 s13, s13, 6
	s_add_i32 s2, s12, s13
	s_add_u32 s8, s8, 0x70000
	s_addc_u32 s9, s9, 0
	v_mov_b32_e32 v0, s2
	v_mov_b32_e32 v1, 1
	s_waitcnt vmcnt(0) lgkmcnt(0)
	global_atomic_add v0, v1, s[8:9]
	s_mov_b64 exec, -1
	s_mov_b32 s2, -1
	v_mbcnt_lo_u32_b32 v0, s2, 0
	v_mbcnt_hi_u32_b32 v0, s2, v0
	v_lshlrev_b32_e32 v0, 6, v0
	v_add_u32_e32 v0, s12, v0
	s_mov_b32 s100, 0
.Lmy_g8_spin:
	global_load_dword v2, v0, s[8:9] sc1
	s_waitcnt vmcnt(0)
	v_cmp_gt_u32_e32 vcc, 4, v2
	s_cmp_eq_u64 vcc, 0
	s_cbranch_scc1 .Lmy_g8_done
	s_sleep 2
	s_add_i32 s100, s100, 1
	s_cmp_lt_u32 s100, 0x2000
	s_cbranch_scc1 .Lmy_g8_spin
.Lmy_g8_done:
	s_mov_b64 exec, 1
	s_branch .Lmy_to51
